# MLA fast loop: compiler lgkmcnt wait ladders collapsed (one wait per MFMA pair in QK, one per 4-MFMA step in PV): 22 fewer issue slots per tile per wave
# speedup vs baseline: 1.0036x; 1.0036x over previous
; #define LAS __attribute__((address_space(3)))
; template <int DQ>
; DI void attn_item(const Frame& F, const AttnItem& it, const LAS float* rpb_lds) {
;     ...
;     auto lstore = [&](int ti) {
;         LAS unsigned char* kb = base + (ti & 1) * KBYTES; LAS unsigned char* vb = base + 2 * KBYTES + (ti % 3) * VBYTES;
; #pragma unroll
;         for (int i = 0; i < 2; ++i) { const int id = tid + i * NT; *(LAS u32x4*)(kb + ((id >> 4) * KP + (id & 15) * 8) * 2) = rk[i];
;             *(LAS u32x4*)(vb + ((id >> 3) * VP + (id & 7) * 8) * 2) = rv[i]; }
;         if (DQ == 192) *(LAS u32x4*)(kb + ((tid >> 3) * KP + 128 + (tid & 7) * 8) * 2) = rr;
;     };
;     ...
;     auto qk = [&](int ti) {
;         if (!active(ti)) return;
;         const int krow_l = (qq & 3) + 4 * ((qq >> 3) & 1) + 8 * ((qq >> 2) & 1) + 16 * (qq >> 4);
;         LAS unsigned char* kb = base + (ti & 1) * KBYTES + (krow_l * KP + 8 * hh) * 2;
; #pragma unroll
;         for (int blk = 0; blk < 2; ++blk)
; #pragma unroll
;             for (int i = 0; i < 16; ++i) s[blk][i] = 0.f;
;         bf16x8 kf[3][2];
; #pragma unroll
;         for (int p = 0; p < 2; ++p)
; #pragma unroll
;             for (int blk = 0; blk < 2; ++blk) kf[p][blk] = *(const LAS bf16x8*)(kb + (32 * blk * KP + 16 * p) * 2);
; #pragma unroll
;         for (int ks = 0; ks < KS; ++ks) {
;             if (ks + 2 < KS) {
; #pragma unroll
;                 for (int blk = 0; blk < 2; ++blk) kf[(ks + 2) % 3][blk] = *(const LAS bf16x8*)(kb + (32 * blk * KP + 16 * (ks + 2)) * 2); }
;             __builtin_amdgcn_sched_barrier(0);
; #pragma unroll
;             for (int blk = 0; blk < 2; ++blk) s[blk] = __builtin_amdgcn_mfma_f32_32x32x16_bf16(kf[ks % 3][blk], qf[ks], s[blk], 0, 0, 0);
;             __builtin_amdgcn_sched_barrier(0);
;         }
;     };
.Lfast_1347:
	s_mul_hi_u32 s4, s17, 0xaaaaaaab
	s_lshr_b32 s4, s4, 1
	s_mul_i32 s4, s4, 0xd800
	s_and_b32 s12, 1, s18
	v_subrev_u32_e32 v180, s4, v213
	v_subrev_u32_e32 v181, s4, v214
	s_cselect_b32 s4, 0x6400, 0
	v_add_u32_e32 v182, s4, v212
	ds_read_b128 v[80:83], v182 offset:12800
	ds_read_b128 v[84:87], v182
	ds_read_b128 v[176:179], v182 offset:32
	ds_read_b128 v[218:221], v182 offset:12832
	ds_read_b128 v[222:225], v182 offset:64
	ds_read_b128 v[226:229], v182 offset:12864
	s_waitcnt lgkmcnt(4)
	v_mfma_f32_32x32x16_bf16 v[96:111], v[84:87], v[144:147], 0
	v_mfma_f32_32x32x16_bf16 v[80:95], v[80:83], v[144:147], 0
	ds_read_b128 v[230:233], v182 offset:96
	ds_read_b128 v[234:237], v182 offset:12896
	s_waitcnt lgkmcnt(4)
	v_mfma_f32_32x32x16_bf16 v[96:111], v[176:179], v[140:143], v[96:111]
	v_mfma_f32_32x32x16_bf16 v[80:95], v[218:221], v[140:143], v[80:95]
	ds_read_b128 v[176:179], v182 offset:128
	ds_read_b128 v[218:221], v182 offset:12928
	s_waitcnt lgkmcnt(4)
	v_mfma_f32_32x32x16_bf16 v[96:111], v[222:225], v[136:139], v[96:111]
	v_mfma_f32_32x32x16_bf16 v[80:95], v[226:229], v[136:139], v[80:95]
	ds_read_b128 v[222:225], v182 offset:160
	ds_read_b128 v[226:229], v182 offset:12960
	s_waitcnt lgkmcnt(4)
	v_mfma_f32_32x32x16_bf16 v[96:111], v[230:233], v[132:135], v[96:111]
	v_mfma_f32_32x32x16_bf16 v[80:95], v[234:237], v[132:135], v[80:95]
	ds_read_b128 v[230:233], v182 offset:192
	ds_read_b128 v[234:237], v182 offset:12992
	s_waitcnt lgkmcnt(4)
	v_mfma_f32_32x32x16_bf16 v[96:111], v[176:179], v[128:131], v[96:111]
	v_mfma_f32_32x32x16_bf16 v[80:95], v[218:221], v[128:131], v[80:95]
	ds_read_b128 v[176:179], v182 offset:224
	ds_read_b128 v[218:221], v182 offset:13024
	s_waitcnt lgkmcnt(4)
	v_mfma_f32_32x32x16_bf16 v[96:111], v[222:225], v[124:127], v[96:111]
	v_mfma_f32_32x32x16_bf16 v[80:95], v[226:229], v[124:127], v[80:95]
	ds_read_b128 v[222:225], v182 offset:256
	ds_read_b128 v[226:229], v182 offset:13056
	s_waitcnt lgkmcnt(4)
	v_mfma_f32_32x32x16_bf16 v[96:111], v[230:233], v[120:123], v[96:111]
	v_mfma_f32_32x32x16_bf16 v[80:95], v[234:237], v[120:123], v[80:95]
	ds_read_b128 v[230:233], v182 offset:288
	ds_read_b128 v[234:237], v182 offset:13088
	s_waitcnt lgkmcnt(4)
	v_mfma_f32_32x32x16_bf16 v[96:111], v[176:179], v[116:119], v[96:111]
	v_mfma_f32_32x32x16_bf16 v[80:95], v[218:221], v[116:119], v[80:95]
	ds_read_b128 v[176:179], v182 offset:320
	ds_read_b128 v[218:221], v182 offset:13120
	s_waitcnt lgkmcnt(4)
	v_mfma_f32_32x32x16_bf16 v[96:111], v[222:225], v[112:115], v[96:111]
	v_mfma_f32_32x32x16_bf16 v[80:95], v[226:229], v[112:115], v[80:95]
	ds_read_b128 v[222:225], v182 offset:352
	ds_read_b128 v[226:229], v182 offset:13152
	s_waitcnt lgkmcnt(0)
	v_mfma_f32_32x32x16_bf16 v[96:111], v[230:233], v[10:13], v[96:111]
	v_mfma_f32_32x32x16_bf16 v[80:95], v[234:237], v[10:13], v[80:95]
	v_mfma_f32_32x32x16_bf16 v[96:111], v[176:179], v[6:9], v[96:111]
	v_mfma_f32_32x32x16_bf16 v[80:95], v[218:221], v[6:9], v[80:95]
	v_mfma_f32_32x32x16_bf16 v[96:111], v[222:225], v[2:5], v[96:111]
	v_mfma_f32_32x32x16_bf16 v[80:95], v[226:229], v[2:5], v[80:95]
	v_cndmask_b32_e64 v176, 0, 1, s[8:9]
	v_cmp_ne_u32_e64 s[4:5], 1, v176
	s_andn2_b64 vcc, exec, s[8:9]
	v_add_u32_e32 v218, 0, v181
	v_add_u32_e32 v205, 0, v180
	s_cbranch_vccnz .Lfast_1353
	s_cmp_eq_u32 s12, 1
	s_cselect_b32 s6, 0, 0x6400
	s_add_i32 s6, s6, 0
	v_add_u32_e32 v176, s6, v209
	s_waitcnt vmcnt(0)
	ds_write_b128 v176, v[164:167]
	s_waitcnt vmcnt(3)
	ds_write_b128 v218, v[160:163]
	v_add_u32_e32 v160, s6, v210
	s_waitcnt vmcnt(2)
	ds_write_b128 v160, v[156:159]
	s_waitcnt vmcnt(1)
	ds_write_b128 v205, v[152:155]
	v_add_u32_e32 v152, s6, v211
	s_cmp_ge_u32 s18, s3
	s_mov_b64 s[6:7], -1
	s_waitcnt vmcnt(0)
	ds_write_b128 v152, v[148:151]
	s_cbranch_scc0 .Lfast_1350
	s_add_i32 s6, s15, s19
	s_add_i32 s13, s6, 0xfffff000
	s_mov_b64 s[6:7], 0

; #define LAS __attribute__((address_space(3)))
; DI unsigned pk2(float a, float b) { f32x2 v = {a, b}; bfv2 r = __builtin_convertvector(v, bfv2); return __builtin_bit_cast(unsigned, r); }
; template <int DQ>
; DI void attn_item(const Frame& F, const AttnItem& it, const LAS float* rpb_lds) {
;     ...
;         const float mnew = fmaxf(mrun, mx), alpha = __builtin_amdgcn_exp2f(mrun - mnew);
;         mrun = mnew;
;         float ps = 0.f;
; #pragma unroll
;         for (int blk = 0; blk < 2; ++blk)
; #pragma unroll
;             for (int i = 0; i < 16; ++i) { const float p = __builtin_amdgcn_exp2f(s[blk][i] - mnew); s[blk][i] = p; ps += p; }
;         lrun = lrun * alpha + ps;
;         if (__builtin_amdgcn_ballot_w64(alpha != 1.f) != 0ull) {
; #pragma unroll
;             for (int db = 0; db < 4; ++db)
; #pragma unroll
;                 for (int i = 0; i < 16; ++i) o[db][i] *= alpha;
;         }
;         LAS unsigned char* vq = vb + (qq * VP + 8 * hh) * 2;
;         auto vload = [&](int step, int db) { return *(const LAS bf16x8*)(vq + (32 * db * VP + 16 * step) * 2); };
;         bf16x8 vf[2][4];
; #pragma unroll
;         for (int db = 0; db < 4; ++db) vf[0][db] = vload(0, db);
; #pragma unroll
;         for (int st = 0; st < 4; ++st) {
;             if (st + 1 < 4) {
; #pragma unroll
;                 for (int db = 0; db < 4; ++db) vf[(st + 1) & 1][db] = vload(st + 1, db); }
;             __builtin_amdgcn_sched_barrier(0);
;             const int blk = st >> 1, s2 = st & 1;
;             u32x4 pw; pw.x = pk2(s[blk][8 * s2], s[blk][8 * s2 + 1]); pw.y = pk2(s[blk][8 * s2 + 2], s[blk][8 * s2 + 3]);
;             pw.z = pk2(s[blk][8 * s2 + 4], s[blk][8 * s2 + 5]); pw.w = pk2(s[blk][8 * s2 + 6], s[blk][8 * s2 + 7]);
;             const bf16x8 pf = __builtin_bit_cast(bf16x8, pw);
; #pragma unroll
;             for (int db = 0; db < 4; ++db) o[db] = __builtin_amdgcn_mfma_f32_32x32x16_bf16(vf[st & 1][db], pf, o[db], 0, 0, 0);
;             __builtin_amdgcn_sched_barrier(0);
;         }
;     ...
;         if (grpB) { if (ti + 1 < ntile) lstore(ti + 1); if (ti + 2 < ntile) gload(ti + 2); __syncthreads(); }
;         smpv(ti);
;         if (!grpB) { if (ti + 1 < ntile) lstore(ti + 1); if (ti + 2 < ntile) gload(ti + 2); __syncthreads(); }
.Lfast_1355:
	s_mul_hi_u32 s6, s16, 0xaaaaaaab
	s_lshr_b32 s6, s6, 1
	s_mul_i32 s6, s6, 0xd800
	v_subrev_u32_e32 v176, s6, v215
	v_add_u32_e32 v180, 0, v176
	ds_read_b128 v[176:179], v180 offset:4608
	ds_read_b128 v[220:223], v180 offset:9216
	ds_read_b128 v[224:227], v180 offset:13824
	ds_read_b128 v[228:231], v180
	ds_read_b128 v[232:235], v180 offset:32
	ds_read_b128 v[236:239], v180 offset:4640
	ds_read_b128 v[240:243], v180 offset:9248
	ds_read_b128 v[244:247], v180 offset:13856
	v_exp_f32_e32 v96, v96
	v_exp_f32_e32 v97, v97
	v_exp_f32_e32 v98, v98
	v_exp_f32_e32 v99, v99
	v_exp_f32_e32 v100, v100
	v_exp_f32_e32 v101, v101
	v_exp_f32_e32 v102, v102
	v_exp_f32_e32 v103, v103
	v_cvt_pk_bf16_f32 v248, v96, v97
	v_cvt_pk_bf16_f32 v249, v98, v99
	v_cvt_pk_bf16_f32 v250, v100, v101
	v_cvt_pk_bf16_f32 v251, v102, v103
	s_waitcnt lgkmcnt(4)
	s_nop 0
	v_mfma_f32_32x32x16_bf16 v[64:79], v[228:231], v[248:251], v[64:79]
	v_exp_f32_e32 v104, v104
	v_exp_f32_e32 v105, v105
	v_mfma_f32_32x32x16_bf16 v[48:63], v[176:179], v[248:251], v[48:63]
	v_exp_f32_e32 v106, v106
	v_exp_f32_e32 v107, v107
	v_mfma_f32_32x32x16_bf16 v[32:47], v[220:223], v[248:251], v[32:47]
	v_exp_f32_e32 v108, v108
	v_exp_f32_e32 v109, v109
	v_mfma_f32_32x32x16_bf16 v[16:31], v[224:227], v[248:251], v[16:31]
	v_exp_f32_e32 v110, v110
	v_exp_f32_e32 v111, v111
	ds_read_b128 v[176:179], v180 offset:64
	ds_read_b128 v[220:223], v180 offset:4672
	ds_read_b128 v[224:227], v180 offset:9280
	ds_read_b128 v[228:231], v180 offset:13888
	v_cvt_pk_bf16_f32 v248, v104, v105
	v_cvt_pk_bf16_f32 v249, v106, v107
	v_cvt_pk_bf16_f32 v250, v108, v109
	v_cvt_pk_bf16_f32 v251, v110, v111
	s_waitcnt lgkmcnt(4)
	s_nop 0
	v_mfma_f32_32x32x16_bf16 v[64:79], v[232:235], v[248:251], v[64:79]
	v_exp_f32_e32 v80, v80
	v_exp_f32_e32 v81, v81
	v_add_f32_e32 v96, v97, v96
	v_add_f32_e32 v98, v99, v98
	v_mfma_f32_32x32x16_bf16 v[48:63], v[236:239], v[248:251], v[48:63]
	v_exp_f32_e32 v82, v82
	v_exp_f32_e32 v83, v83
	v_add_f32_e32 v100, v101, v100
	v_add_f32_e32 v102, v103, v102
	v_mfma_f32_32x32x16_bf16 v[32:47], v[240:243], v[248:251], v[32:47]
	v_exp_f32_e32 v84, v84
	v_exp_f32_e32 v85, v85
	v_add_f32_e32 v96, v98, v96
	v_add_f32_e32 v100, v102, v100
	v_mfma_f32_32x32x16_bf16 v[16:31], v[244:247], v[248:251], v[16:31]
	v_exp_f32_e32 v86, v86
	v_exp_f32_e32 v87, v87
	v_add_f32_e32 v96, v100, v96
	ds_read_b128 v[232:235], v180 offset:96
	ds_read_b128 v[236:239], v180 offset:4704
	ds_read_b128 v[240:243], v180 offset:9312
	ds_read_b128 v[244:247], v180 offset:13920
	v_cvt_pk_bf16_f32 v248, v80, v81
	v_cvt_pk_bf16_f32 v249, v82, v83
	v_cvt_pk_bf16_f32 v250, v84, v85
	v_cvt_pk_bf16_f32 v251, v86, v87
	s_waitcnt lgkmcnt(4)
	s_nop 0
	v_mfma_f32_32x32x16_bf16 v[64:79], v[176:179], v[248:251], v[64:79]
	v_exp_f32_e32 v88, v88
	v_exp_f32_e32 v89, v89
	v_add_f32_e32 v104, v105, v104
	v_add_f32_e32 v106, v107, v106
	v_mfma_f32_32x32x16_bf16 v[48:63], v[220:223], v[248:251], v[48:63]
	v_exp_f32_e32 v90, v90
	v_exp_f32_e32 v91, v91
	v_add_f32_e32 v108, v109, v108
	v_add_f32_e32 v110, v111, v110
	v_mfma_f32_32x32x16_bf16 v[32:47], v[224:227], v[248:251], v[32:47]
	v_exp_f32_e32 v92, v92
	v_exp_f32_e32 v93, v93
	v_add_f32_e32 v104, v106, v104
	v_add_f32_e32 v108, v110, v108
	v_mfma_f32_32x32x16_bf16 v[16:31], v[228:231], v[248:251], v[16:31]
	v_exp_f32_e32 v94, v94
	v_exp_f32_e32 v95, v95
	v_add_f32_e32 v104, v108, v104
	v_cvt_pk_bf16_f32 v176, v88, v89
	v_cvt_pk_bf16_f32 v177, v90, v91
	v_cvt_pk_bf16_f32 v178, v92, v93
	v_cvt_pk_bf16_f32 v179, v94, v95
	s_waitcnt lgkmcnt(0)
	s_nop 0
	v_mfma_f32_32x32x16_bf16 v[64:79], v[232:235], v[176:179], v[64:79]
	v_add_f32_e32 v80, v81, v80
	v_add_f32_e32 v82, v83, v82
	v_add_f32_e32 v84, v85, v84
	v_add_f32_e32 v86, v87, v86
	v_add_f32_e32 v88, v89, v88
	v_add_f32_e32 v90, v91, v90
	v_mfma_f32_32x32x16_bf16 v[48:63], v[236:239], v[176:179], v[48:63]
	v_add_f32_e32 v92, v93, v92
	v_add_f32_e32 v94, v95, v94
	v_add_f32_e32 v80, v82, v80
	v_add_f32_e32 v84, v86, v84
	v_add_f32_e32 v88, v90, v88
	v_add_f32_e32 v92, v94, v92
	v_mfma_f32_32x32x16_bf16 v[32:47], v[240:243], v[176:179], v[32:47]
	v_add_f32_e32 v80, v84, v80
	v_add_f32_e32 v88, v92, v88
	v_add_f32_e32 v96, v104, v96
	v_mfma_f32_32x32x16_bf16 v[16:31], v[244:247], v[176:179], v[16:31]
	v_add_f32_e32 v80, v88, v80
	v_add_f32_e32 v96, v80, v96
	v_cndmask_b32_e64 v176, 0, 1, s[10:11]
	v_cmp_ne_u32_e64 s[6:7], 1, v176
	s_andn2_b64 vcc, exec, s[10:11]
	s_cbranch_vccnz .Lfast_1361
	s_cmp_eq_u32 s12, 1
	s_cselect_b32 s12, 0, 0x6400
	s_add_i32 s12, s12, 0
	v_add_u32_e32 v176, s12, v209
	s_waitcnt vmcnt(0)
	ds_write_b128 v176, v[164:167]
	ds_write_b128 v218, v[160:163]
	v_add_u32_e32 v160, s12, v210
	ds_write_b128 v160, v[156:159]
	ds_write_b128 v205, v[152:155]
	v_add_u32_e32 v152, s12, v211
	s_cmp_ge_u32 s18, s3
	s_mov_b64 s[12:13], -1
	ds_write_b128 v152, v[148:151]
	s_cbranch_scc0 .Lfast_1358
	s_add_i32 s12, s15, s19
	s_add_i32 s21, s12, 0xfffff000
	s_mov_b64 s[12:13], 0
